# in-proj epilogue: rotary-key cos/sin loads issued as one burst; silu N-tiles rebalanced over workgroup classes
# speedup vs baseline: 1.0028x; 1.0028x over previous
.LBB0_412:
	s_andn2_b64 vcc, exec, s[62:63]
	s_cbranch_vccnz .LBB0_414
	s_waitcnt lgkmcnt(0)
	v_lshlrev_b64 v[66:67], 6, v[136:137]
	v_lshl_add_u64 v[68:69], v[144:145], 0, v[66:67]
	v_lshl_add_u64 v[72:73], v[142:143], 0, v[66:67]
	global_load_dwordx4 v[82:85], v[68:69], off
	global_load_dwordx4 v[86:89], v[72:73], off
	s_mov_b64 s[16:17], 0x400
	v_lshl_add_u64 v[76:77], v[66:67], 0, s[16:17]
	v_lshl_add_u64 v[68:69], v[144:145], 0, v[76:77]
	v_lshl_add_u64 v[72:73], v[142:143], 0, v[76:77]
	global_load_dwordx4 v[90:93], v[68:69], off
	global_load_dwordx4 v[94:97], v[72:73], off
	v_lshl_add_u64 v[76:77], v[66:67], 0, s[36:37]
	v_lshl_add_u64 v[68:69], v[144:145], 0, v[76:77]
	v_lshl_add_u64 v[72:73], v[142:143], 0, v[76:77]
	global_load_dwordx4 v[98:101], v[68:69], off
	global_load_dwordx4 v[102:105], v[72:73], off
	s_mov_b64 s[16:17], 0xc00
	v_lshl_add_u64 v[76:77], v[66:67], 0, s[16:17]
	v_lshl_add_u64 v[68:69], v[144:145], 0, v[76:77]
	v_lshl_add_u64 v[72:73], v[142:143], 0, v[76:77]
	global_load_dwordx4 v[106:109], v[68:69], off
	global_load_dwordx4 v[110:113], v[72:73], off
	v_lshl_add_u64 v[76:77], v[66:67], 0, s[68:69]
	v_lshl_add_u64 v[68:69], v[144:145], 0, v[76:77]
	v_lshl_add_u64 v[72:73], v[142:143], 0, v[76:77]
	global_load_dwordx4 v[114:117], v[68:69], off
	global_load_dwordx4 v[118:121], v[72:73], off
	s_mov_b64 s[16:17], 0x2400
	v_lshl_add_u64 v[76:77], v[66:67], 0, s[16:17]
	v_lshl_add_u64 v[68:69], v[144:145], 0, v[76:77]
	v_lshl_add_u64 v[72:73], v[142:143], 0, v[76:77]
	global_load_dwordx4 v[122:125], v[68:69], off
	global_load_dwordx4 v[126:129], v[72:73], off
	s_mov_b64 s[16:17], 0x2800
	v_lshl_add_u64 v[76:77], v[66:67], 0, s[16:17]
	v_lshl_add_u64 v[68:69], v[144:145], 0, v[76:77]
	v_lshl_add_u64 v[72:73], v[142:143], 0, v[76:77]
	global_load_dwordx4 v[226:229], v[68:69], off
	global_load_dwordx4 v[230:233], v[72:73], off
	s_mov_b64 s[16:17], 0x2c00
	v_lshl_add_u64 v[76:77], v[66:67], 0, s[16:17]
	v_lshl_add_u64 v[68:69], v[144:145], 0, v[76:77]
	v_lshl_add_u64 v[72:73], v[142:143], 0, v[76:77]
	global_load_dwordx4 v[234:237], v[68:69], off
	global_load_dwordx4 v[238:241], v[72:73], off
	s_waitcnt vmcnt(14)
	v_pk_mul_f32 v[76:77], v[60:61], v[88:89]
	v_pk_mul_f32 v[78:79], v[58:59], v[86:87]
	v_pk_mul_f32 v[74:75], v[64:65], v[88:89]
	v_pk_mul_f32 v[72:73], v[62:63], v[86:87]
	v_pk_fma_f32 v[76:77], v[64:65], v[84:85], v[76:77] neg_lo:[0,0,1] neg_hi:[0,0,1]
	v_pk_fma_f32 v[78:79], v[62:63], v[82:83], v[78:79] neg_lo:[0,0,1] neg_hi:[0,0,1]
	v_pk_fma_f32 v[70:71], v[60:61], v[84:85], v[74:75]
	v_pk_fma_f32 v[68:69], v[58:59], v[82:83], v[72:73]
	v_lshl_add_u64 v[72:73], v[140:141], 0, v[66:67]
	v_cvt_pk_bf16_f32 v74, v78, v79
	v_cvt_pk_bf16_f32 v75, v76, v77
	v_cvt_pk_bf16_f32 v68, v68, v69
	v_cvt_pk_bf16_f32 v69, v70, v71
	global_store_dwordx2 v[72:73], v[74:75], off
	global_store_dwordx2 v[72:73], v[68:69], off offset:32
	s_waitcnt vmcnt(14)
	v_pk_mul_f32 v[76:77], v[52:53], v[96:97]
	v_pk_mul_f32 v[78:79], v[50:51], v[94:95]
	v_pk_mul_f32 v[74:75], v[56:57], v[96:97]
	v_pk_mul_f32 v[72:73], v[54:55], v[94:95]
	v_pk_fma_f32 v[76:77], v[56:57], v[92:93], v[76:77] neg_lo:[0,0,1] neg_hi:[0,0,1]
	v_pk_fma_f32 v[78:79], v[54:55], v[90:91], v[78:79] neg_lo:[0,0,1] neg_hi:[0,0,1]
	v_pk_fma_f32 v[70:71], v[52:53], v[92:93], v[74:75]
	v_pk_fma_f32 v[68:69], v[50:51], v[90:91], v[72:73]
	s_mov_b64 s[16:17], 0x400
	v_lshl_add_u64 v[80:81], v[66:67], 0, s[16:17]
	v_lshl_add_u64 v[72:73], v[140:141], 0, v[80:81]
	v_cvt_pk_bf16_f32 v74, v78, v79
	v_cvt_pk_bf16_f32 v75, v76, v77
	v_cvt_pk_bf16_f32 v68, v68, v69
	v_cvt_pk_bf16_f32 v69, v70, v71
	global_store_dwordx2 v[72:73], v[74:75], off
	global_store_dwordx2 v[72:73], v[68:69], off offset:32
	s_waitcnt vmcnt(14)
	v_pk_mul_f32 v[76:77], v[44:45], v[104:105]
	v_pk_mul_f32 v[78:79], v[42:43], v[102:103]
	v_pk_mul_f32 v[74:75], v[48:49], v[104:105]
	v_pk_mul_f32 v[72:73], v[46:47], v[102:103]
	v_pk_fma_f32 v[76:77], v[48:49], v[100:101], v[76:77] neg_lo:[0,0,1] neg_hi:[0,0,1]
	v_pk_fma_f32 v[78:79], v[46:47], v[98:99], v[78:79] neg_lo:[0,0,1] neg_hi:[0,0,1]
	v_pk_fma_f32 v[70:71], v[44:45], v[100:101], v[74:75]
	v_pk_fma_f32 v[68:69], v[42:43], v[98:99], v[72:73]
	v_lshl_add_u64 v[80:81], v[66:67], 0, s[36:37]
	v_lshl_add_u64 v[72:73], v[140:141], 0, v[80:81]
	v_cvt_pk_bf16_f32 v74, v78, v79
	v_cvt_pk_bf16_f32 v75, v76, v77
	v_cvt_pk_bf16_f32 v68, v68, v69
	v_cvt_pk_bf16_f32 v69, v70, v71
	global_store_dwordx2 v[72:73], v[74:75], off
	global_store_dwordx2 v[72:73], v[68:69], off offset:32
	s_waitcnt vmcnt(14)
	v_pk_mul_f32 v[76:77], v[36:37], v[112:113]
	v_pk_mul_f32 v[78:79], v[34:35], v[110:111]
	v_pk_mul_f32 v[74:75], v[40:41], v[112:113]
	v_pk_mul_f32 v[72:73], v[38:39], v[110:111]
	v_pk_fma_f32 v[76:77], v[40:41], v[108:109], v[76:77] neg_lo:[0,0,1] neg_hi:[0,0,1]
	v_pk_fma_f32 v[78:79], v[38:39], v[106:107], v[78:79] neg_lo:[0,0,1] neg_hi:[0,0,1]
	v_pk_fma_f32 v[70:71], v[36:37], v[108:109], v[74:75]
	v_pk_fma_f32 v[68:69], v[34:35], v[106:107], v[72:73]
	s_mov_b64 s[16:17], 0xc00
	v_lshl_add_u64 v[80:81], v[66:67], 0, s[16:17]
	v_lshl_add_u64 v[72:73], v[140:141], 0, v[80:81]
	v_cvt_pk_bf16_f32 v74, v78, v79
	v_cvt_pk_bf16_f32 v75, v76, v77
	v_cvt_pk_bf16_f32 v68, v68, v69
	v_cvt_pk_bf16_f32 v69, v70, v71
	global_store_dwordx2 v[72:73], v[74:75], off
	global_store_dwordx2 v[72:73], v[68:69], off offset:32
	s_waitcnt vmcnt(14)
	v_pk_mul_f32 v[76:77], v[28:29], v[120:121]
	v_pk_mul_f32 v[78:79], v[26:27], v[118:119]
	v_pk_mul_f32 v[74:75], v[32:33], v[120:121]
	v_pk_mul_f32 v[72:73], v[30:31], v[118:119]
	v_pk_fma_f32 v[76:77], v[32:33], v[116:117], v[76:77] neg_lo:[0,0,1] neg_hi:[0,0,1]
	v_pk_fma_f32 v[78:79], v[30:31], v[114:115], v[78:79] neg_lo:[0,0,1] neg_hi:[0,0,1]
	v_pk_fma_f32 v[70:71], v[28:29], v[116:117], v[74:75]
	v_pk_fma_f32 v[68:69], v[26:27], v[114:115], v[72:73]
	v_lshl_add_u64 v[80:81], v[66:67], 0, s[68:69]
	v_lshl_add_u64 v[72:73], v[140:141], 0, v[80:81]
	v_cvt_pk_bf16_f32 v74, v78, v79
	v_cvt_pk_bf16_f32 v75, v76, v77
	v_cvt_pk_bf16_f32 v68, v68, v69
	v_cvt_pk_bf16_f32 v69, v70, v71
	global_store_dwordx2 v[72:73], v[74:75], off
	global_store_dwordx2 v[72:73], v[68:69], off offset:32
	s_waitcnt vmcnt(14)
	v_pk_mul_f32 v[76:77], v[20:21], v[128:129]
	v_pk_mul_f32 v[78:79], v[18:19], v[126:127]
	v_pk_mul_f32 v[74:75], v[24:25], v[128:129]
	v_pk_mul_f32 v[72:73], v[22:23], v[126:127]
	v_pk_fma_f32 v[76:77], v[24:25], v[124:125], v[76:77] neg_lo:[0,0,1] neg_hi:[0,0,1]
	v_pk_fma_f32 v[78:79], v[22:23], v[122:123], v[78:79] neg_lo:[0,0,1] neg_hi:[0,0,1]
	v_pk_fma_f32 v[70:71], v[20:21], v[124:125], v[74:75]
	v_pk_fma_f32 v[68:69], v[18:19], v[122:123], v[72:73]
	s_mov_b64 s[16:17], 0x2400
	v_lshl_add_u64 v[80:81], v[66:67], 0, s[16:17]
	v_lshl_add_u64 v[72:73], v[140:141], 0, v[80:81]
	v_cvt_pk_bf16_f32 v74, v78, v79
	v_cvt_pk_bf16_f32 v75, v76, v77
	v_cvt_pk_bf16_f32 v68, v68, v69
	v_cvt_pk_bf16_f32 v69, v70, v71
	global_store_dwordx2 v[72:73], v[74:75], off
	global_store_dwordx2 v[72:73], v[68:69], off offset:32
	s_waitcnt vmcnt(14)
	v_pk_mul_f32 v[76:77], v[10:11], v[232:233]
	v_pk_mul_f32 v[78:79], v[8:9], v[230:231]
	v_pk_mul_f32 v[74:75], v[16:17], v[232:233]
	v_pk_mul_f32 v[72:73], v[14:15], v[230:231]
	v_pk_fma_f32 v[76:77], v[16:17], v[228:229], v[76:77] neg_lo:[0,0,1] neg_hi:[0,0,1]
	v_pk_fma_f32 v[78:79], v[14:15], v[226:227], v[78:79] neg_lo:[0,0,1] neg_hi:[0,0,1]
	v_pk_fma_f32 v[70:71], v[10:11], v[228:229], v[74:75]
	v_pk_fma_f32 v[68:69], v[8:9], v[226:227], v[72:73]
	s_mov_b64 s[16:17], 0x2800
	v_lshl_add_u64 v[80:81], v[66:67], 0, s[16:17]
	v_lshl_add_u64 v[72:73], v[140:141], 0, v[80:81]
	v_cvt_pk_bf16_f32 v74, v78, v79
	v_cvt_pk_bf16_f32 v75, v76, v77
	v_cvt_pk_bf16_f32 v68, v68, v69
	v_cvt_pk_bf16_f32 v69, v70, v71
	global_store_dwordx2 v[72:73], v[74:75], off
	global_store_dwordx2 v[72:73], v[68:69], off offset:32
	s_waitcnt vmcnt(14)
	v_pk_mul_f32 v[76:77], v[2:3], v[240:241]
	v_pk_mul_f32 v[78:79], v[0:1], v[238:239]
	v_pk_mul_f32 v[74:75], v[6:7], v[240:241]
	v_pk_mul_f32 v[72:73], v[4:5], v[238:239]
	v_pk_fma_f32 v[76:77], v[6:7], v[236:237], v[76:77] neg_lo:[0,0,1] neg_hi:[0,0,1]
	v_pk_fma_f32 v[78:79], v[4:5], v[234:235], v[78:79] neg_lo:[0,0,1] neg_hi:[0,0,1]
	v_pk_fma_f32 v[70:71], v[2:3], v[236:237], v[74:75]
	v_pk_fma_f32 v[68:69], v[0:1], v[234:235], v[72:73]
	s_mov_b64 s[16:17], 0x2c00
	v_lshl_add_u64 v[80:81], v[66:67], 0, s[16:17]
	v_lshl_add_u64 v[72:73], v[140:141], 0, v[80:81]
	v_cvt_pk_bf16_f32 v74, v78, v79
	v_cvt_pk_bf16_f32 v75, v76, v77
	v_cvt_pk_bf16_f32 v68, v68, v69
	v_cvt_pk_bf16_f32 v69, v70, v71
	global_store_dwordx2 v[72:73], v[74:75], off
	global_store_dwordx2 v[72:73], v[68:69], off offset:32
